# previous combination + rw_mix and rw_outprep row loops with all loads issued up front (load hoists)
# baseline (speedup 1.0000x reference)
.LBB0_217:
	s_or_b64 exec, exec, s[8:9]
	global_load_dwordx4 v[72:75], v[18:19], off
	global_load_dwordx4 v[76:79], v[18:19], off offset:16
	s_mov_b32 s0, 0x2100000
	v_add_u32_e32 v48, s50, v48
	global_load_dwordx4 v[80:83], v[18:19], off offset:32
	global_load_dwordx4 v[84:87], v[18:19], off offset:48
	v_add_co_u32_e32 v88, vcc, s0, v30
	s_mov_b32 s0, 0x4200000
	v_addc_co_u32_e32 v89, vcc, 0, v31, vcc
	global_load_dwordx4 v[90:93], v[20:21], off
	global_load_dwordx4 v[94:97], v[20:21], off offset:16
	global_load_dwordx4 v[98:101], v[20:21], off offset:32
	global_load_dwordx4 v[120:123], v[20:21], off offset:48
	global_load_dwordx4 v[124:127], v[22:23], off
	global_load_dwordx4 v[128:131], v[22:23], off offset:16
	v_add_co_u32_e32 v102, vcc, s0, v30
	s_mov_b32 s0, 0x6300000
	v_addc_co_u32_e32 v103, vcc, 0, v31, vcc
	global_load_dwordx4 v[132:135], v[22:23], off offset:32
	global_load_dwordx4 v[136:139], v[22:23], off offset:48
	global_load_dwordx4 v[140:143], v[24:25], off
	global_load_dwordx4 v[144:147], v[24:25], off offset:16
	v_add_co_u32_e32 v148, vcc, s0, v30
	s_mov_b32 s0, 0x8400000
	v_addc_co_u32_e32 v149, vcc, 0, v31, vcc
	global_load_dwordx4 v[150:153], v[24:25], off offset:32
	global_load_dwordx4 v[154:157], v[24:25], off offset:48
	global_load_dwordx4 v[158:161], v[26:27], off
	global_load_dwordx4 v[162:165], v[26:27], off offset:16
	v_add_co_u32_e32 v166, vcc, s0, v30
	s_mov_b32 s0, 0xa500000
	v_addc_co_u32_e32 v167, vcc, 0, v31, vcc
	global_load_dwordx4 v[168:171], v[26:27], off offset:32
	global_load_dwordx4 v[172:175], v[26:27], off offset:48
	global_load_dwordx4 v[176:179], v[28:29], off
	global_load_dwordx4 v[184:187], v[28:29], off offset:16
	v_add_co_u32_e32 v188, vcc, s0, v30
	v_addc_co_u32_e32 v189, vcc, 0, v31, vcc
	global_load_dwordx4 v[190:193], v[28:29], off offset:32
	global_load_dwordx4 v[194:197], v[28:29], off offset:48
	v_cmp_lt_i32_e32 vcc, s4, v48
	s_or_b64 s[24:25], vcc, s[24:25]
	s_waitcnt vmcnt(0)
	v_and_b32_e32 v199, 0xffff0000, v8
	v_lshlrev_b32_e32 v198, 16, v8
	v_and_b32_e32 v201, 0xffff0000, v12
	v_lshlrev_b32_e32 v200, 16, v12
	v_and_b32_e32 v203, 0xffff0000, v9
	v_lshlrev_b32_e32 v202, 16, v9
	v_and_b32_e32 v205, 0xffff0000, v13
	v_lshlrev_b32_e32 v204, 16, v13
	v_and_b32_e32 v207, 0xffff0000, v10
	v_lshlrev_b32_e32 v206, 16, v10
	v_and_b32_e32 v209, 0xffff0000, v14
	v_lshlrev_b32_e32 v208, 16, v14
	v_and_b32_e32 v211, 0xffff0000, v11
	v_lshlrev_b32_e32 v210, 16, v11
	v_and_b32_e32 v213, 0xffff0000, v15
	v_lshlrev_b32_e32 v212, 16, v15
	v_pk_add_f32 v[214:215], v[200:201], v[198:199] neg_lo:[0,1] neg_hi:[0,1]
	v_pk_add_f32 v[200:201], v[204:205], v[202:203] neg_lo:[0,1] neg_hi:[0,1]
	v_pk_add_f32 v[204:205], v[208:209], v[206:207] neg_lo:[0,1] neg_hi:[0,1]
	v_pk_add_f32 v[208:209], v[212:213], v[210:211] neg_lo:[0,1] neg_hi:[0,1]
	v_and_b32_e32 v213, 0xffff0000, v2
	v_lshlrev_b32_e32 v212, 16, v2
	v_and_b32_e32 v217, 0xffff0000, v3
	v_lshlrev_b32_e32 v216, 16, v3
	v_pk_fma_f32 v[218:219], v[214:215], v[72:73], v[198:199]
	v_pk_fma_f32 v[220:221], v[200:201], v[74:75], v[202:203]
	v_pk_fma_f32 v[72:73], v[204:205], v[76:77], v[206:207]
	v_pk_fma_f32 v[74:75], v[208:209], v[78:79], v[210:211]
	v_cvt_pk_bf16_f32 v76, v218, v219
	v_cvt_pk_bf16_f32 v77, v220, v221
	v_cvt_pk_bf16_f32 v78, v72, v73
	v_cvt_pk_bf16_f32 v79, v74, v75
	global_store_dwordx4 v[30:31], v[76:79], off
	v_and_b32_e32 v73, 0xffff0000, v4
	v_lshlrev_b32_e32 v72, 16, v4
	v_and_b32_e32 v75, 0xffff0000, v0
	v_lshlrev_b32_e32 v74, 16, v0
	v_and_b32_e32 v77, 0xffff0000, v5
	v_lshlrev_b32_e32 v76, 16, v5
	v_and_b32_e32 v79, 0xffff0000, v1
	v_lshlrev_b32_e32 v78, 16, v1
	v_and_b32_e32 v219, 0xffff0000, v6
	v_lshlrev_b32_e32 v218, 16, v6
	v_and_b32_e32 v221, 0xffff0000, v7
	v_lshlrev_b32_e32 v220, 16, v7
	v_pk_add_f32 v[222:223], v[74:75], v[72:73] neg_lo:[0,1] neg_hi:[0,1]
	v_pk_add_f32 v[74:75], v[78:79], v[76:77] neg_lo:[0,1] neg_hi:[0,1]
	v_pk_add_f32 v[78:79], v[212:213], v[218:219] neg_lo:[0,1] neg_hi:[0,1]
	v_pk_add_f32 v[212:213], v[216:217], v[220:221] neg_lo:[0,1] neg_hi:[0,1]
	v_pk_fma_f32 v[216:217], v[222:223], v[80:81], v[72:73]
	v_pk_fma_f32 v[224:225], v[74:75], v[82:83], v[76:77]
	v_pk_fma_f32 v[80:81], v[78:79], v[84:85], v[218:219]
	v_pk_fma_f32 v[82:83], v[212:213], v[86:87], v[220:221]
	v_cvt_pk_bf16_f32 v84, v216, v217
	v_cvt_pk_bf16_f32 v85, v224, v225
	v_cvt_pk_bf16_f32 v86, v80, v81
	v_cvt_pk_bf16_f32 v87, v82, v83
	global_store_dwordx4 v[30:31], v[84:87], off offset:16
	v_pk_fma_f32 v[80:81], v[214:215], v[90:91], v[198:199]
	v_pk_fma_f32 v[82:83], v[200:201], v[92:93], v[202:203]
	v_pk_fma_f32 v[84:85], v[204:205], v[94:95], v[206:207]
	v_pk_fma_f32 v[86:87], v[208:209], v[96:97], v[210:211]
	v_cvt_pk_bf16_f32 v90, v80, v81
	v_cvt_pk_bf16_f32 v91, v82, v83
	v_cvt_pk_bf16_f32 v92, v84, v85
	v_cvt_pk_bf16_f32 v93, v86, v87
	global_store_dwordx4 v[88:89], v[90:93], off
	v_pk_fma_f32 v[80:81], v[222:223], v[98:99], v[72:73]
	v_pk_fma_f32 v[82:83], v[74:75], v[100:101], v[76:77]
	v_pk_fma_f32 v[84:85], v[78:79], v[120:121], v[218:219]
	v_pk_fma_f32 v[86:87], v[212:213], v[122:123], v[220:221]
	v_cvt_pk_bf16_f32 v90, v80, v81
	v_cvt_pk_bf16_f32 v91, v82, v83
	v_cvt_pk_bf16_f32 v92, v84, v85
	v_cvt_pk_bf16_f32 v93, v86, v87
	global_store_dwordx4 v[88:89], v[90:93], off offset:16
	v_pk_fma_f32 v[80:81], v[214:215], v[124:125], v[198:199]
	v_pk_fma_f32 v[82:83], v[200:201], v[126:127], v[202:203]
	v_pk_fma_f32 v[84:85], v[204:205], v[128:129], v[206:207]
	v_pk_fma_f32 v[86:87], v[208:209], v[130:131], v[210:211]
	v_cvt_pk_bf16_f32 v88, v80, v81
	v_cvt_pk_bf16_f32 v89, v82, v83
	v_cvt_pk_bf16_f32 v90, v84, v85
	v_cvt_pk_bf16_f32 v91, v86, v87
	global_store_dwordx4 v[102:103], v[88:91], off
	v_pk_fma_f32 v[80:81], v[222:223], v[132:133], v[72:73]
	v_pk_fma_f32 v[82:83], v[74:75], v[134:135], v[76:77]
	v_pk_fma_f32 v[84:85], v[78:79], v[136:137], v[218:219]
	v_pk_fma_f32 v[86:87], v[212:213], v[138:139], v[220:221]
	v_cvt_pk_bf16_f32 v88, v80, v81
	v_cvt_pk_bf16_f32 v89, v82, v83
	v_cvt_pk_bf16_f32 v90, v84, v85
	v_cvt_pk_bf16_f32 v91, v86, v87
	global_store_dwordx4 v[102:103], v[88:91], off offset:16
	v_pk_fma_f32 v[80:81], v[214:215], v[140:141], v[198:199]
	v_pk_fma_f32 v[82:83], v[200:201], v[142:143], v[202:203]
	v_pk_fma_f32 v[84:85], v[204:205], v[144:145], v[206:207]
	v_pk_fma_f32 v[86:87], v[208:209], v[146:147], v[210:211]
	v_cvt_pk_bf16_f32 v88, v80, v81
	v_cvt_pk_bf16_f32 v89, v82, v83
	v_cvt_pk_bf16_f32 v90, v84, v85
	v_cvt_pk_bf16_f32 v91, v86, v87
	global_store_dwordx4 v[148:149], v[88:91], off
	v_pk_fma_f32 v[80:81], v[222:223], v[150:151], v[72:73]
	v_pk_fma_f32 v[82:83], v[74:75], v[152:153], v[76:77]
	v_pk_fma_f32 v[84:85], v[78:79], v[154:155], v[218:219]
	v_pk_fma_f32 v[86:87], v[212:213], v[156:157], v[220:221]
	v_cvt_pk_bf16_f32 v88, v80, v81
	v_cvt_pk_bf16_f32 v89, v82, v83
	v_cvt_pk_bf16_f32 v90, v84, v85
	v_cvt_pk_bf16_f32 v91, v86, v87
	global_store_dwordx4 v[148:149], v[88:91], off offset:16
	v_pk_fma_f32 v[80:81], v[214:215], v[158:159], v[198:199]
	v_pk_fma_f32 v[82:83], v[200:201], v[160:161], v[202:203]
	v_pk_fma_f32 v[84:85], v[204:205], v[162:163], v[206:207]
	v_pk_fma_f32 v[86:87], v[208:209], v[164:165], v[210:211]
	v_cvt_pk_bf16_f32 v88, v80, v81
	v_cvt_pk_bf16_f32 v89, v82, v83
	v_cvt_pk_bf16_f32 v90, v84, v85
	v_cvt_pk_bf16_f32 v91, v86, v87
	global_store_dwordx4 v[166:167], v[88:91], off
	v_pk_fma_f32 v[80:81], v[222:223], v[168:169], v[72:73]
	v_pk_fma_f32 v[82:83], v[74:75], v[170:171], v[76:77]
	v_pk_fma_f32 v[84:85], v[78:79], v[172:173], v[218:219]
	v_pk_fma_f32 v[86:87], v[212:213], v[174:175], v[220:221]
	v_cvt_pk_bf16_f32 v88, v80, v81
	v_cvt_pk_bf16_f32 v89, v82, v83
	v_cvt_pk_bf16_f32 v90, v84, v85
	v_cvt_pk_bf16_f32 v91, v86, v87
	global_store_dwordx4 v[166:167], v[88:91], off offset:16
	v_pk_fma_f32 v[80:81], v[214:215], v[176:177], v[198:199]
	v_pk_fma_f32 v[82:83], v[200:201], v[178:179], v[202:203]
	v_pk_fma_f32 v[84:85], v[204:205], v[184:185], v[206:207]
	v_pk_fma_f32 v[86:87], v[208:209], v[186:187], v[210:211]
	v_cvt_pk_bf16_f32 v88, v80, v81
	v_cvt_pk_bf16_f32 v89, v82, v83
	v_cvt_pk_bf16_f32 v90, v84, v85
	v_cvt_pk_bf16_f32 v91, v86, v87
	global_store_dwordx4 v[188:189], v[88:91], off
	v_lshl_add_u64 v[30:31], v[30:31], 0, s[26:27]
	v_pk_fma_f32 v[80:81], v[222:223], v[190:191], v[72:73]
	v_pk_fma_f32 v[72:73], v[74:75], v[192:193], v[76:77]
	v_pk_fma_f32 v[74:75], v[78:79], v[194:195], v[218:219]
	v_pk_fma_f32 v[76:77], v[212:213], v[196:197], v[220:221]
	v_cvt_pk_bf16_f32 v82, v80, v81
	v_cvt_pk_bf16_f32 v83, v72, v73
	v_cvt_pk_bf16_f32 v84, v74, v75
	v_cvt_pk_bf16_f32 v85, v76, v77
	global_store_dwordx4 v[188:189], v[82:85], off offset:16
	s_andn2_b64 exec, exec, s[24:25]
	s_cbranch_execz .LBB0_248
